# static s_setprio 1 for waves 4-7 also during P4 (retention outputs + merge)
# speedup vs baseline: 1.0087x; 1.0063x over previous
.LBB0_530:
	s_or_b64 exec, exec, s[0:1]
	v_readfirstlane_b32 s98, v222
	s_cmp_ge_u32 s98, 0x100
	s_cbranch_scc0 .Lprio_p4
	s_setprio 1
.Lprio_p4:
	v_mov_b32_e32 v120, v222
	s_and_b64 vcc, exec, s[4:5]
	s_waitcnt lgkmcnt(0)
	s_barrier
	s_cbranch_vccz .LBB0_538
	s_lshl_b64 s[0:1], s[88:89], 13
	s_add_u32 s0, s8, s0
	s_addc_u32 s1, s9, s1
	s_lshl_b32 s2, s88, 2
	s_and_b32 s2, s2, 0x380
	s_add_u32 s2, s68, s2
	s_addc_u32 s3, s69, 0
	s_ashr_i32 s4, s88, 8
	s_ashr_i32 s5, s4, 31
	s_lshl_b32 s12, s88, 7
	s_lshl_b64 s[4:5], s[4:5], 12
	s_and_b32 s12, s12, 0xf80
	s_waitcnt vmcnt(8)
	v_lshlrev_b32_e32 v22, 3, v120
	s_waitcnt vmcnt(6)
	v_lshlrev_b32_e32 v30, 4, v120
	v_ashrrev_i32_e32 v94, 3, v120
	v_add_u32_e32 v14, 0x200, v120
	s_or_b32 s4, s4, s12
	v_and_b32_e32 v92, 0x70, v30
	v_mov_b32_e32 v93, 0
	v_ashrrev_i32_e32 v95, 31, v94
	v_ashrrev_i32_e32 v96, 3, v14
	v_and_b32_e32 v22, 0xffffffc0, v22
	v_lshl_add_u64 v[12:13], s[2:3], 0, v[92:93]
	v_lshl_add_u64 v[0:1], s[4:5], 0, v[94:95]
	s_movk_i32 s17, 0x1c00
	v_ashrrev_i32_e32 v97, 31, v96
	v_ashrrev_i32_e32 v23, 31, v22
	v_mad_u64_u32 v[8:9], s[2:3], v0, s17, v[12:13]
	v_lshl_add_u64 v[14:15], s[4:5], 0, v[96:97]
	v_lshlrev_b64 v[28:29], 1, v[22:23]
	v_mad_i32_i24 v9, v1, s17, v9
	v_mad_u64_u32 v[20:21], s[2:3], v14, s17, v[12:13]
	v_lshl_add_u64 v[22:23], s[0:1], 0, v[28:29]
	global_load_dwordx4 v[0:3], v[8:9], off
	global_load_dwordx4 v[4:7], v[8:9], off offset:1024
	s_nop 0
	global_load_dwordx4 v[8:11], v[8:9], off offset:2048
	v_mad_i32_i24 v21, v15, s17, v21
	v_lshl_add_u64 v[24:25], v[22:23], 0, v[92:93]
	global_load_dwordx4 v[12:15], v[20:21], off offset:1024
	global_load_dwordx4 v[16:19], v[20:21], off offset:2048
	s_nop 0
	global_load_dwordx4 v[20:23], v[20:21], off
	s_nop 0
	global_load_dwordx4 v[24:27], v[24:25], off
	v_lshl_add_u64 v[28:29], s[8:9], 0, v[28:29]
	v_lshl_add_u64 v[100:101], v[28:29], 0, v[92:93]
	v_and_b32_e32 v28, 48, v30
	v_lshlrev_b32_e32 v30, 1, v28
	v_mov_b32_e32 v31, v93
	v_lshl_add_u64 v[104:105], s[6:7], 0, v[30:31]
	v_bfe_u32 v29, v120, 4, 2
	v_bfe_u32 v31, v120, 2, 2
	s_movk_i32 s33, 0x90
	v_and_b32_e32 v123, 15, v120
	s_waitcnt vmcnt(12)
	v_lshl_or_b32 v34, v29, 3, v31
	v_mad_u32_u24 v124, v34, s33, 0
	v_lshlrev_b32_e32 v34, 3, v123
	v_and_b32_e32 v125, 24, v34
	v_or_b32_e32 v126, 0x60, v34
	v_mbcnt_hi_u32_b32 v34, -1, v223
	s_waitcnt vmcnt(11)
	v_and_b32_e32 v36, 64, v34
	v_xor_b32_e32 v35, 16, v34
	v_add_u32_e32 v36, 64, v36
	v_cmp_lt_i32_e32 vcc, v35, v36
	v_mul_u32_u24_e32 v31, 0x90, v31
	s_movk_i32 s0, 0x240
	v_cndmask_b32_e32 v35, v34, v35, vcc
	v_lshlrev_b32_e32 v128, 2, v35
	v_xor_b32_e32 v35, 32, v34
	v_mul_lo_u32 v122, v94, s33
	v_lshlrev_b32_e32 v30, 4, v29
	v_lshlrev_b32_e32 v127, 2, v29
	v_cmp_lt_i32_e32 vcc, v35, v36
	v_mad_u32_u24 v29, v29, s0, v31
	v_add_u32_e32 v121, 0, v92
	v_mul_lo_u32 v32, v96, s33
	v_add_u32_e32 v33, 0, v122
	v_ashrrev_i32_e32 v102, 2, v120
	v_cndmask_b32_e32 v34, v34, v35, vcc
	v_add_u32_e32 v130, v29, v126
	v_add_u32_e32 v131, v29, v125
	v_mul_u32_u24_e32 v29, 0x90, v123
	s_movk_i32 s0, 0x4800
	s_mov_b32 s3, 0
	v_lshl_add_u64 v[98:99], s[68:69], 0, v[92:93]
	v_ashrrev_i32_e32 v103, 31, v102
	v_lshlrev_b32_e32 v129, 2, v34
	v_add_u32_e32 v106, 0, v30
	v_add3_u32 v132, v29, v30, s0
	v_sub_u32_e32 v133, v123, v127
	v_add_u32_e32 v134, v121, v32
	v_add_u32_e32 v135, v33, v92
	s_mov_b32 s40, 0x800000
	s_mov_b32 s41, 0x3f317217
	s_mov_b32 s42, 0x7f800000
	s_mov_b64 s[12:13], 0x4000
	s_mov_b64 s[14:15], 0x8000
	s_mov_b32 s16, 0x3e000000
	s_mov_b32 s43, 0x5040100
	v_mov_b32_e32 v136, 0x358637bd
	v_lshlrev_b32_e32 v108, 1, v28
	v_mov_b32_e32 v137, 0x41b17218
	s_mov_b32 s0, s88
	s_branch .LBB0_533

.LBB0_538:
	s_setprio 0
	s_barrier
	s_waitcnt vmcnt(0)
	s_barrier
	s_mov_b64 s[0:1], exec
	v_readlane_b32 s2, v247, 4
	v_readlane_b32 s3, v247, 5
	s_and_b64 s[2:3], s[0:1], s[2:3]
	v_readlane_b32 s68, v247, 16
	s_xor_b64 s[0:1], s[2:3], s[0:1]
	v_readlane_b32 s69, v247, 17
	s_mov_b64 exec, s[2:3]
	s_cbranch_execz .LBB0_591
	s_add_i32 s2, 0, 0x23ff0
	v_mov_b32_e32 v0, s2
	s_waitcnt vmcnt(0) expcnt(0) lgkmcnt(0)
	ds_read_b32 v2, v0
	s_add_i32 s2, 0, 0x23ff4
	v_mov_b32_e32 v0, s2
	ds_read_b32 v0, v0
	s_waitcnt lgkmcnt(1)
	v_cmp_ne_u32_e32 vcc, 0, v2
	s_cbranch_vccnz .LBB0_554
	v_readlane_b32 s2, v247, 0
	s_mul_i32 s33, s27, s2
	s_add_u32 s2, s24, 0x1e00200
	s_addc_u32 s3, s25, 0
	s_add_u32 s4, s24, 0x1e00400
	s_addc_u32 s5, s25, 0
	s_add_u32 s6, s24, 0x1e00500
	s_addc_u32 s7, s25, 0
	s_add_u32 s8, s24, 0x1e00600
	s_addc_u32 s9, s25, 0
	s_add_u32 s10, s24, 0x1e00700
	s_addc_u32 s11, s25, 0
	s_add_u32 s12, s24, 0x1e00800
	s_addc_u32 s13, s25, 0
	s_add_u32 s14, s24, 0x1e00900
	s_addc_u32 s15, s25, 0
	s_add_u32 s16, s24, 0x1e00a00
	s_addc_u32 s17, s25, 0
	s_add_u32 s18, s24, 0x1e00b00
	s_addc_u32 s19, s25, 0
	s_add_u32 s30, s24, 0x1e00c00
	s_addc_u32 s31, s25, 0
	s_add_u32 s34, s24, 0x1e00d00
	s_addc_u32 s35, s25, 0
	s_add_u32 s36, s24, 0x1e00e00
	s_addc_u32 s37, s25, 0
	s_add_u32 s38, s24, 0x1e00f00
	s_addc_u32 s39, s25, 0
	s_add_u32 s40, s24, 0x1e01000
	s_addc_u32 s41, s25, 0
	s_add_u32 s42, s24, 0x1e01100
	s_addc_u32 s43, s25, 0
	s_add_u32 s44, s24, 0x1e01200
	s_addc_u32 s45, s25, 0
	s_add_u32 s50, s24, 0x1e01300
	s_mul_i32 s33, s33, s26
	s_addc_u32 s51, s25, 0
	s_mov_b32 s58, 1
	v_mov_b32_e32 v16, 0
	s_branch .LBB0_542
